# phase 0: ab_w_in converted by the lean LDS-free routine (compiler tr_run skipped)
# speedup vs baseline: 1.0051x; 1.0006x over previous
; #define LAS __attribute__((address_space(3)))
; __device__ __forceinline__ bf16_t f2bf(float f) { return (bf16_t)(cvt_pk_bf16(f, 0.f) & 0xffffu); }
; __device__ __forceinline__ void phase_p0(const Params& p, LAS unsigned char* lds, int gw, int ngw, int wave, int lane) {
;     unsigned char* ws = p.ws;
;     LAS float* scr = (LAS float*)(lds + wave * 8704);
;     { P0Item pi{&p, 0}; tr_run<P0Item, false>(pi, gw, ngw, P0A_ITEMS, scr, lane); }
;     { bf16_t* WS_ = (bf16_t*)(ws + WS_WSMALL);
;       for (int i = gw * 64 + lane; i < 32 * DM; i += ngw * 64) { const int c = i & 31, k = i >> 5; const int sc = c < 16 ? 6144 + c : 12304 + (c - 16);
;           WS_[(size_t)c * DM + k] = f2bf(p.ab_w_in[(size_t)k * AB_IN + sc] * p.norm_mix[k]); } }
.LBB0_11:
	s_or_b64 exec, exec, s[2:3]
	v_readlane_b32 s2, v240, 1
	s_lshr_b32 s6, s2, 6
	v_readlane_b32 s2, v240, 0
	s_mov_b32 s4, s6
	s_lshl_b32 s2, s2, 3
	v_writelane_b32 v240, s4, 25
	s_lshl_b32 s36, s92, 3
	s_add_i32 s2, s6, s2
	v_writelane_b32 v240, s5, 26
	v_writelane_b32 v240, s2, 27
	s_cmp_lt_i32 s40, 1
	v_and_b32_e32 v164, 63, v0
	v_writelane_b32 v240, s3, 28
	s_cselect_b64 s[2:3], -1, 0
	s_cmp_gt_i32 s41, 0
	s_cselect_b64 s[4:5], -1, 0
	s_and_b64 s[2:3], s[2:3], s[4:5]
	s_andn2_b64 vcc, exec, s[2:3]
	s_cbranch_vccnz .LBB0_120
	s_branch .LBB0_58
.LBB0_15:
.LBB0_18:
.LBB0_19:
.LBB0_20:
.LBB0_21:
.LBB0_22:
.LBB0_23:
.LBB0_26:
.LBB0_27:
.LBB0_28:
.LBB0_29:
.LBB0_31:
.LBB0_32:
.LBB0_34:
.LBB0_35:
.LBB0_36:
.LBB0_38:
.LBB0_39:
.LBB0_40:
.LBB0_41:
.LBB0_43:
.LBB0_44:
.LBB0_45:
.LBB0_46:
.LBB0_47:
.LBB0_48:
.LBB0_49:
.LBB0_51:
.LBB0_52:
.LBB0_53:
.LBB0_54:
.LBB0_56:
.LBB0_57:
.LBB0_58:
	v_readlane_b32 s2, v240, 27
	v_readlane_b32 s3, v240, 28
	s_waitcnt vmcnt(6)
	v_lshl_or_b32 v8, s2, 6, v164
	s_mov_b32 s2, 0x20000
	v_cmp_gt_i32_e32 vcc, s2, v8
	s_and_saveexec_b64 s[2:3], vcc
	s_load_dwordx16 s[12:27], s[0:1], 0x0
	s_cbranch_execz .LBB0_61
	v_and_b32_e32 v2, 31, v0
	v_mov_b32_e32 v3, 0x3000
	v_mov_b32_e32 v4, 0x1800
	v_cmp_gt_u32_e32 vcc, 16, v2
	s_mov_b64 s[4:5], 0x2f500000
	s_lshl_b32 s6, s92, 9
	v_cndmask_b32_e32 v3, v3, v4, vcc
	v_or_b32_e32 v6, v3, v2
	v_lshlrev_b32_e32 v2, 13, v2
	v_mov_b32_e32 v3, 0
	v_lshl_add_u64 v[4:5], s[58:59], 0, v[2:3]
	v_lshlrev_b32_e32 v2, 2, v6
	v_lshl_add_u64 v[4:5], v[4:5], 0, s[4:5]
	s_waitcnt lgkmcnt(0)
	v_lshl_add_u64 v[6:7], s[24:25], 0, v[2:3]
	s_mov_b64 s[4:5], 0
	s_mov_b32 s7, 0xc080
	s_mov_b32 s8, 0x1ffff

; __device__ __forceinline__ TrDesc p0_item(const Params& p, int it) {
;     ...
;     TR_JOB(p.ab_w_in, AB_IN, DM, 0, 6144, WAB_IN, 0, p.norm_mix)
;     TR_JOB(p.ab_w_in, AB_IN, DM, 6160, 6144, WAB_IN, 6144, p.norm_mix)
.Lpz_job_abi0:
	s_load_dwordx2 s[60:61], s[82:83], 0x30
	s_load_dwordx2 s[62:63], s[82:83], 0xb8
	s_load_dwordx2 s[76:77], s[82:83], 0x8
	s_mov_b32 s78, 0xc080
	s_mov_b32 s79, 0x2000
	s_mov_b32 s75, 0
	s_and_b32 s84, s81, 63
	s_lshr_b32 s85, s81, 6
	s_add_i32 s85, s85, 0
	s_and_b32 s85, s85, 31
	s_sub_i32 s74, 47, s85
	s_lshr_b32 s74, s74, 5
	s_add_i32 s74, s74, 1
	s_lshl_b32 s86, s84, 6
	s_mul_i32 s86, s86, s78
	s_lshl_b32 s87, s85, 9
	s_add_u32 s86, s86, s87
	s_mul_i32 s88, s85, 128
	s_mul_i32 s88, s88, s79
	s_lshl_b32 s89, s84, 7
	s_add_u32 s88, s88, s89
	s_mov_b32 s70, 0x4000
	s_mov_b32 s71, 0
	s_mov_b32 s72, 0x2000000
	s_mov_b32 s73, 0
	s_waitcnt lgkmcnt(0)
	s_add_u32 s60, s60, s86
	s_addc_u32 s61, s61, 0
	s_add_u32 s62, s62, 0x100000
	s_addc_u32 s63, s63, 0
	s_add_u32 s62, s62, s88
	s_addc_u32 s63, s63, 0
	s_lshl_b32 s89, s79, 5
	s_add_u32 s64, s62, s89
	s_addc_u32 s65, s63, 0
	s_add_u32 s66, s64, s89
	s_addc_u32 s67, s65, 0
	s_add_u32 s68, s66, s89
	s_addc_u32 s69, s67, 0
	s_lshl_b32 s89, s84, 8
	s_add_u32 s76, s76, s89
	s_addc_u32 s77, s77, 0
	s_mov_b32 s80, 1
	s_branch .Lpz_run
.Lpz_back_0:
.Lpz_job_abi1:
	s_load_dwordx2 s[60:61], s[82:83], 0x30
	s_load_dwordx2 s[62:63], s[82:83], 0xb8
	s_load_dwordx2 s[76:77], s[82:83], 0x8
	s_mov_b32 s78, 0xc080
	s_mov_b32 s79, 0x2000
	s_mov_b32 s75, 1
	s_and_b32 s84, s81, 63
	s_lshr_b32 s85, s81, 6
	s_add_i32 s85, s85, 16
	s_and_b32 s85, s85, 31
	s_sub_i32 s74, 47, s85
	s_lshr_b32 s74, s74, 5
	s_add_i32 s74, s74, 1
	s_lshl_b32 s86, s84, 6
	s_mul_i32 s86, s86, s78
	s_lshl_b32 s87, s85, 9
	s_add_u32 s86, s86, s87
	s_mul_i32 s88, s85, 128
	s_add_i32 s88, s88, 6144
	s_mul_i32 s88, s88, s79
	s_lshl_b32 s89, s84, 7
	s_add_u32 s88, s88, s89
	s_mov_b32 s70, 0x4000
	s_mov_b32 s71, 0
	s_mov_b32 s72, 0x2000000
	s_mov_b32 s73, 0
	s_waitcnt lgkmcnt(0)
	s_add_u32 s60, s60, 0x6040
	s_addc_u32 s61, s61, 0
	s_add_u32 s60, s60, s86
	s_addc_u32 s61, s61, 0
	s_add_u32 s62, s62, 0x100000
	s_addc_u32 s63, s63, 0
	s_add_u32 s62, s62, s88
	s_addc_u32 s63, s63, 0
	s_lshl_b32 s89, s79, 5
	s_add_u32 s64, s62, s89
	s_addc_u32 s65, s63, 0
	s_add_u32 s66, s64, s89
	s_addc_u32 s67, s65, 0
	s_add_u32 s68, s66, s89
	s_addc_u32 s69, s67, 0
	s_lshl_b32 s89, s84, 8
	s_add_u32 s76, s76, s89
	s_addc_u32 s77, s77, 0
	s_mov_b32 s80, 1
	s_branch .Lpz_run

; #define LAS __attribute__((address_space(3)))
; __device__ __forceinline__ void phase_p0(const Params& p, LAS unsigned char* lds, int gw, int ngw, int wave, int lane) {
;     unsigned char* ws = p.ws;
;     LAS float* scr = (LAS float*)(lds + wave * 8704);
;     { P0Item pi{&p, 0}; tr_run<P0Item, false>(pi, gw, ngw, P0A_ITEMS, scr, lane); }
.Lpz_ret:
	s_cmp_eq_u32 s75, 0
	s_cbranch_scc1 .Lpz_back_0
	s_cmp_eq_u32 s75, 1
	s_cbranch_scc1 .Lpz_back_1
.Lpz_done:
	s_branch .Lpz_resume
